# QKV epilogue rope blocks rewritten as 4 pk_mul + 4 pk_fma each (was 27 instr), f32 unchanged
# speedup vs baseline: 1.0032x; 1.0032x over previous
.LBB0_139:
	s_waitcnt vmcnt(0)
	v_pk_add_f32 v[222:223], v[166:167], v[78:79]
	v_pk_add_f32 v[164:165], v[164:165], v[76:77]
	v_pk_add_f32 v[220:221], v[162:163], v[70:71]
	v_pk_add_f32 v[166:167], v[160:161], v[68:69]
	s_and_saveexec_b64 s[34:35], s[8:9]
	s_cbranch_execz .LBB0_141
	v_pk_mul_f32 v[224:225], v[164:165], v[188:189] op_sel:[1,0] op_sel_hi:[0,0]
	v_pk_mul_f32 v[226:227], v[222:223], v[188:189] op_sel:[1,1] op_sel_hi:[0,1]
	v_pk_mul_f32 v[238:239], v[166:167], v[190:191] op_sel:[1,0] op_sel_hi:[0,0]
	v_pk_mul_f32 v[240:241], v[220:221], v[190:191] op_sel:[1,1] op_sel_hi:[0,1]
	v_pk_fma_f32 v[164:165], v[164:165], v[184:185], v[224:225] op_sel_hi:[1,0,1] neg_lo:[0,0,1]
	v_pk_fma_f32 v[222:223], v[222:223], v[184:185], v[226:227] op_sel:[0,1,0] op_sel_hi:[1,1,1] neg_lo:[0,0,1]
	v_pk_fma_f32 v[166:167], v[166:167], v[186:187], v[238:239] op_sel_hi:[1,0,1] neg_lo:[0,0,1]
	v_pk_fma_f32 v[220:221], v[220:221], v[186:187], v[240:241] op_sel:[0,1,0] op_sel_hi:[1,1,1] neg_lo:[0,0,1]
.LBB0_141:
	s_or_b64 exec, exec, s[34:35]
	v_readlane_b32 s21, v255, 18
	s_cmp_lt_i32 s28, 4
	s_cselect_b64 vcc, -1, 0
	v_mad_u64_u32 v[162:163], s[28:29], v218, s21, 0
	v_mov_b32_e32 v218, v163
	v_mov_b32_e32 v160, 0x3e38aa3b
	v_mad_u64_u32 v[218:219], s[28:29], v219, s21, v[218:219]
	v_cndmask_b32_e32 v160, 1.0, v160, vcc
	v_mov_b32_e32 v163, v218
	v_lshl_add_u64 v[162:163], v[162:163], 1, s[96:97]
	v_pk_mul_f32 v[218:219], v[160:161], v[222:223] op_sel_hi:[0,1]
	v_pk_mul_f32 v[164:165], v[160:161], v[164:165] op_sel_hi:[0,1]
	v_pk_mul_f32 v[220:221], v[160:161], v[220:221] op_sel_hi:[0,1]
	v_pk_mul_f32 v[166:167], v[160:161], v[166:167] op_sel_hi:[0,1]
	v_lshl_add_u64 v[162:163], v[208:209], 1, v[162:163]
	v_cvt_pk_bf16_f32 v164, v164, v165
	v_cvt_pk_bf16_f32 v165, v218, v219
	v_cvt_pk_bf16_f32 v166, v166, v167
	v_cvt_pk_bf16_f32 v167, v220, v221
	global_store_dwordx4 v[162:163], v[164:167], off
	v_pk_add_f32 v[148:149], v[148:149], v[60:61]
	s_nop 0
	v_pk_add_f32 v[164:165], v[150:151], v[62:63]
	v_pk_add_f32 v[150:151], v[146:147], v[58:59]
	v_pk_add_f32 v[146:147], v[144:145], v[56:57]
	s_and_saveexec_b64 s[28:29], s[8:9]
	s_cbranch_execz .LBB0_143
	v_pk_mul_f32 v[224:225], v[148:149], v[188:189] op_sel:[1,0] op_sel_hi:[0,0]
	v_pk_mul_f32 v[226:227], v[164:165], v[188:189] op_sel:[1,1] op_sel_hi:[0,1]
	v_pk_mul_f32 v[238:239], v[146:147], v[190:191] op_sel:[1,0] op_sel_hi:[0,0]
	v_pk_mul_f32 v[240:241], v[150:151], v[190:191] op_sel:[1,1] op_sel_hi:[0,1]
	v_pk_fma_f32 v[148:149], v[148:149], v[184:185], v[224:225] op_sel_hi:[1,0,1] neg_lo:[0,0,1]
	v_pk_fma_f32 v[164:165], v[164:165], v[184:185], v[226:227] op_sel:[0,1,0] op_sel_hi:[1,1,1] neg_lo:[0,0,1]
	v_pk_fma_f32 v[146:147], v[146:147], v[186:187], v[238:239] op_sel_hi:[1,0,1] neg_lo:[0,0,1]
	v_pk_fma_f32 v[150:151], v[150:151], v[186:187], v[240:241] op_sel:[0,1,0] op_sel_hi:[1,1,1] neg_lo:[0,0,1]
.LBB0_143:
	s_or_b64 exec, exec, s[28:29]
	v_mov_b32_e32 v161, v160
	v_mov_b32_e32 v144, v160
	v_mov_b32_e32 v145, v160
	v_pk_mul_f32 v[164:165], v[144:145], v[164:165]
	v_pk_mul_f32 v[148:149], v[160:161], v[148:149]
	v_pk_mul_f32 v[150:151], v[144:145], v[150:151]
	v_pk_mul_f32 v[166:167], v[160:161], v[146:147]
	v_cvt_pk_bf16_f32 v146, v148, v149
	v_cvt_pk_bf16_f32 v147, v164, v165
	v_cvt_pk_bf16_f32 v148, v166, v167
	v_cvt_pk_bf16_f32 v149, v150, v151
	global_store_dwordx4 v[162:163], v[146:149], off offset:256
	v_pk_add_f32 v[140:141], v[140:141], v[76:77]
	s_nop 0
	v_pk_add_f32 v[146:147], v[142:143], v[78:79]
	v_pk_add_f32 v[142:143], v[138:139], v[70:71]
	v_pk_add_f32 v[138:139], v[136:137], v[68:69]
	s_and_saveexec_b64 s[28:29], s[8:9]
	s_cbranch_execz .LBB0_145
	v_pk_mul_f32 v[224:225], v[140:141], v[180:181] op_sel:[1,0] op_sel_hi:[0,0]
	v_pk_mul_f32 v[226:227], v[146:147], v[180:181] op_sel:[1,1] op_sel_hi:[0,1]
	v_pk_mul_f32 v[238:239], v[138:139], v[182:183] op_sel:[1,0] op_sel_hi:[0,0]
	v_pk_mul_f32 v[240:241], v[142:143], v[182:183] op_sel:[1,1] op_sel_hi:[0,1]
	v_pk_fma_f32 v[140:141], v[140:141], v[176:177], v[224:225] op_sel_hi:[1,0,1] neg_lo:[0,0,1]
	v_pk_fma_f32 v[146:147], v[146:147], v[176:177], v[226:227] op_sel:[0,1,0] op_sel_hi:[1,1,1] neg_lo:[0,0,1]
	v_pk_fma_f32 v[138:139], v[138:139], v[178:179], v[238:239] op_sel_hi:[1,0,1] neg_lo:[0,0,1]
	v_pk_fma_f32 v[142:143], v[142:143], v[178:179], v[240:241] op_sel:[0,1,0] op_sel_hi:[1,1,1] neg_lo:[0,0,1]
.LBB0_145:
	s_or_b64 exec, exec, s[28:29]
	v_readlane_b32 s21, v255, 18
	v_pk_mul_f32 v[146:147], v[144:145], v[146:147]
	v_pk_mul_f32 v[140:141], v[160:161], v[140:141]
	v_mad_i64_i32 v[136:137], s[28:29], v216, s21, 0
	v_lshl_add_u64 v[136:137], v[136:137], 1, s[96:97]
	v_pk_mul_f32 v[142:143], v[144:145], v[142:143]
	v_pk_mul_f32 v[144:145], v[160:161], v[138:139]
	v_lshl_add_u64 v[136:137], v[208:209], 1, v[136:137]
	v_cvt_pk_bf16_f32 v138, v140, v141
	v_cvt_pk_bf16_f32 v139, v146, v147
	v_cvt_pk_bf16_f32 v140, v144, v145
	v_cvt_pk_bf16_f32 v141, v142, v143
	global_store_dwordx4 v[136:137], v[138:141], off
	v_pk_add_f32 v[128:129], v[128:129], v[60:61]
	s_nop 0
	v_pk_add_f32 v[138:139], v[130:131], v[62:63]
	v_pk_add_f32 v[130:131], v[122:123], v[58:59]
	v_pk_add_f32 v[122:123], v[120:121], v[56:57]
	s_and_saveexec_b64 s[28:29], s[8:9]
	s_cbranch_execz .LBB0_147
	v_pk_mul_f32 v[224:225], v[128:129], v[180:181] op_sel:[1,0] op_sel_hi:[0,0]
	v_pk_mul_f32 v[226:227], v[138:139], v[180:181] op_sel:[1,1] op_sel_hi:[0,1]
	v_pk_mul_f32 v[238:239], v[122:123], v[182:183] op_sel:[1,0] op_sel_hi:[0,0]
	v_pk_mul_f32 v[240:241], v[130:131], v[182:183] op_sel:[1,1] op_sel_hi:[0,1]
	v_pk_fma_f32 v[128:129], v[128:129], v[176:177], v[224:225] op_sel_hi:[1,0,1] neg_lo:[0,0,1]
	v_pk_fma_f32 v[138:139], v[138:139], v[176:177], v[226:227] op_sel:[0,1,0] op_sel_hi:[1,1,1] neg_lo:[0,0,1]
	v_pk_fma_f32 v[122:123], v[122:123], v[178:179], v[238:239] op_sel_hi:[1,0,1] neg_lo:[0,0,1]
	v_pk_fma_f32 v[130:131], v[130:131], v[178:179], v[240:241] op_sel:[0,1,0] op_sel_hi:[1,1,1] neg_lo:[0,0,1]
.LBB0_147:
	s_or_b64 exec, exec, s[28:29]
	v_mov_b32_e32 v120, v160
	v_mov_b32_e32 v121, v160
	v_pk_mul_f32 v[138:139], v[120:121], v[138:139]
	v_pk_mul_f32 v[128:129], v[160:161], v[128:129]
	v_pk_mul_f32 v[140:141], v[120:121], v[130:131]
	v_pk_mul_f32 v[122:123], v[160:161], v[122:123]
	v_cvt_pk_bf16_f32 v128, v128, v129
	v_cvt_pk_bf16_f32 v129, v138, v139
	v_cvt_pk_bf16_f32 v130, v122, v123
	v_cvt_pk_bf16_f32 v131, v140, v141
	v_pk_add_f32 v[122:123], v[118:119], v[78:79]
	v_pk_add_f32 v[116:117], v[116:117], v[76:77]
	v_pk_add_f32 v[118:119], v[114:115], v[70:71]
	v_pk_add_f32 v[114:115], v[112:113], v[68:69]
	global_store_dwordx4 v[136:137], v[128:131], off offset:256
	s_and_saveexec_b64 s[28:29], s[8:9]
	s_cbranch_execz .LBB0_149
	v_pk_mul_f32 v[224:225], v[116:117], v[172:173] op_sel:[1,0] op_sel_hi:[0,0]
	v_pk_mul_f32 v[226:227], v[122:123], v[172:173] op_sel:[1,1] op_sel_hi:[0,1]
	v_pk_mul_f32 v[238:239], v[114:115], v[174:175] op_sel:[1,0] op_sel_hi:[0,0]
	v_pk_mul_f32 v[240:241], v[118:119], v[174:175] op_sel:[1,1] op_sel_hi:[0,1]
	v_pk_fma_f32 v[116:117], v[116:117], v[168:169], v[224:225] op_sel_hi:[1,0,1] neg_lo:[0,0,1]
	v_pk_fma_f32 v[122:123], v[122:123], v[168:169], v[226:227] op_sel:[0,1,0] op_sel_hi:[1,1,1] neg_lo:[0,0,1]
	v_pk_fma_f32 v[114:115], v[114:115], v[170:171], v[238:239] op_sel_hi:[1,0,1] neg_lo:[0,0,1]
	v_pk_fma_f32 v[118:119], v[118:119], v[170:171], v[240:241] op_sel:[0,1,0] op_sel_hi:[1,1,1] neg_lo:[0,0,1]
.LBB0_149:
	s_or_b64 exec, exec, s[28:29]
	v_readlane_b32 s21, v255, 18
	v_pk_mul_f32 v[122:123], v[120:121], v[122:123]
	v_pk_mul_f32 v[116:117], v[160:161], v[116:117]
	v_mad_i64_i32 v[112:113], s[28:29], v214, s21, 0
	v_lshl_add_u64 v[112:113], v[112:113], 1, s[96:97]
	v_pk_mul_f32 v[118:119], v[120:121], v[118:119]
	v_pk_mul_f32 v[120:121], v[160:161], v[114:115]
	v_lshl_add_u64 v[112:113], v[208:209], 1, v[112:113]
	v_cvt_pk_bf16_f32 v114, v116, v117
	v_cvt_pk_bf16_f32 v115, v122, v123
	v_cvt_pk_bf16_f32 v116, v120, v121
	v_cvt_pk_bf16_f32 v117, v118, v119
	global_store_dwordx4 v[112:113], v[114:117], off
	v_pk_add_f32 v[100:101], v[100:101], v[60:61]
	s_nop 0
	v_pk_add_f32 v[114:115], v[102:103], v[62:63]
	v_pk_add_f32 v[102:103], v[98:99], v[58:59]
	v_pk_add_f32 v[98:99], v[96:97], v[56:57]
	s_and_saveexec_b64 s[28:29], s[8:9]
	s_cbranch_execz .LBB0_151
	v_pk_mul_f32 v[224:225], v[100:101], v[172:173] op_sel:[1,0] op_sel_hi:[0,0]
	v_pk_mul_f32 v[226:227], v[114:115], v[172:173] op_sel:[1,1] op_sel_hi:[0,1]
	v_pk_mul_f32 v[238:239], v[98:99], v[174:175] op_sel:[1,0] op_sel_hi:[0,0]
	v_pk_mul_f32 v[240:241], v[102:103], v[174:175] op_sel:[1,1] op_sel_hi:[0,1]
	v_pk_fma_f32 v[100:101], v[100:101], v[168:169], v[224:225] op_sel_hi:[1,0,1] neg_lo:[0,0,1]
	v_pk_fma_f32 v[114:115], v[114:115], v[168:169], v[226:227] op_sel:[0,1,0] op_sel_hi:[1,1,1] neg_lo:[0,0,1]
	v_pk_fma_f32 v[98:99], v[98:99], v[170:171], v[238:239] op_sel_hi:[1,0,1] neg_lo:[0,0,1]
	v_pk_fma_f32 v[102:103], v[102:103], v[170:171], v[240:241] op_sel:[0,1,0] op_sel_hi:[1,1,1] neg_lo:[0,0,1]
.LBB0_151:
	s_or_b64 exec, exec, s[28:29]
	v_mov_b32_e32 v96, v160
	v_mov_b32_e32 v97, v160
	v_pk_mul_f32 v[114:115], v[96:97], v[114:115]
	v_pk_mul_f32 v[100:101], v[160:161], v[100:101]
	v_pk_mul_f32 v[102:103], v[96:97], v[102:103]
	v_pk_mul_f32 v[116:117], v[160:161], v[98:99]
	v_cvt_pk_bf16_f32 v98, v100, v101
	v_cvt_pk_bf16_f32 v99, v114, v115
	v_cvt_pk_bf16_f32 v100, v116, v117
	v_cvt_pk_bf16_f32 v101, v102, v103
	global_store_dwordx4 v[112:113], v[98:101], off offset:256
	v_pk_add_f32 v[92:93], v[92:93], v[76:77]
	s_nop 0
	v_pk_add_f32 v[98:99], v[94:95], v[78:79]
	v_pk_add_f32 v[94:95], v[90:91], v[70:71]
	v_pk_add_f32 v[90:91], v[88:89], v[68:69]
	s_and_saveexec_b64 s[28:29], s[8:9]
	s_cbranch_execz .LBB0_153
	v_pk_mul_f32 v[224:225], v[92:93], v[156:157] op_sel:[1,0] op_sel_hi:[0,0]
	v_pk_mul_f32 v[226:227], v[98:99], v[156:157] op_sel:[1,1] op_sel_hi:[0,1]
	v_pk_mul_f32 v[238:239], v[90:91], v[158:159] op_sel:[1,0] op_sel_hi:[0,0]
	v_pk_mul_f32 v[240:241], v[94:95], v[158:159] op_sel:[1,1] op_sel_hi:[0,1]
	v_pk_fma_f32 v[92:93], v[92:93], v[152:153], v[224:225] op_sel_hi:[1,0,1] neg_lo:[0,0,1]
	v_pk_fma_f32 v[98:99], v[98:99], v[152:153], v[226:227] op_sel:[0,1,0] op_sel_hi:[1,1,1] neg_lo:[0,0,1]
	v_pk_fma_f32 v[90:91], v[90:91], v[154:155], v[238:239] op_sel_hi:[1,0,1] neg_lo:[0,0,1]
	v_pk_fma_f32 v[94:95], v[94:95], v[154:155], v[240:241] op_sel:[0,1,0] op_sel_hi:[1,1,1] neg_lo:[0,0,1]
.LBB0_153:
	s_or_b64 exec, exec, s[28:29]
	v_readlane_b32 s21, v255, 18
	v_pk_mul_f32 v[98:99], v[96:97], v[98:99]
	v_pk_mul_f32 v[92:93], v[160:161], v[92:93]
	v_mad_i64_i32 v[88:89], s[28:29], v212, s21, 0
	v_lshl_add_u64 v[88:89], v[88:89], 1, s[96:97]
	v_pk_mul_f32 v[94:95], v[96:97], v[94:95]
	v_pk_mul_f32 v[96:97], v[160:161], v[90:91]
	v_lshl_add_u64 v[88:89], v[208:209], 1, v[88:89]
	v_cvt_pk_bf16_f32 v90, v92, v93
	v_cvt_pk_bf16_f32 v91, v98, v99
	v_cvt_pk_bf16_f32 v92, v96, v97
	v_cvt_pk_bf16_f32 v93, v94, v95
	v_pk_add_f32 v[86:87], v[86:87], v[62:63]
	v_pk_add_f32 v[84:85], v[84:85], v[60:61]
	v_pk_add_f32 v[82:83], v[82:83], v[58:59]
	v_pk_add_f32 v[80:81], v[80:81], v[56:57]
	global_store_dwordx4 v[88:89], v[90:93], off
	s_and_saveexec_b64 s[28:29], s[8:9]
	s_cbranch_execz .LBB0_155
	v_pk_mul_f32 v[224:225], v[84:85], v[156:157] op_sel:[1,0] op_sel_hi:[0,0]
	v_pk_mul_f32 v[226:227], v[86:87], v[156:157] op_sel:[1,1] op_sel_hi:[0,1]
	v_pk_mul_f32 v[238:239], v[80:81], v[158:159] op_sel:[1,0] op_sel_hi:[0,0]
	v_pk_mul_f32 v[240:241], v[82:83], v[158:159] op_sel:[1,1] op_sel_hi:[0,1]
	v_pk_fma_f32 v[84:85], v[84:85], v[152:153], v[224:225] op_sel_hi:[1,0,1] neg_lo:[0,0,1]
	v_pk_fma_f32 v[86:87], v[86:87], v[152:153], v[226:227] op_sel:[0,1,0] op_sel_hi:[1,1,1] neg_lo:[0,0,1]
	v_pk_fma_f32 v[80:81], v[80:81], v[154:155], v[238:239] op_sel_hi:[1,0,1] neg_lo:[0,0,1]
	v_pk_fma_f32 v[82:83], v[82:83], v[154:155], v[240:241] op_sel:[0,1,0] op_sel_hi:[1,1,1] neg_lo:[0,0,1]

.LBB0_157:
	v_pk_add_f32 v[98:99], v[74:75], v[78:79]
	v_pk_add_f32 v[72:73], v[72:73], v[76:77]
	v_pk_add_f32 v[96:97], v[66:67], v[70:71]
	v_pk_add_f32 v[74:75], v[64:65], v[68:69]
	s_and_saveexec_b64 s[28:29], s[8:9]
	s_cbranch_execz .LBB0_159
	v_pk_mul_f32 v[224:225], v[72:73], v[132:133] op_sel:[1,0] op_sel_hi:[0,0]
	v_pk_mul_f32 v[226:227], v[98:99], v[132:133] op_sel:[1,1] op_sel_hi:[0,1]
	v_pk_mul_f32 v[238:239], v[74:75], v[134:135] op_sel:[1,0] op_sel_hi:[0,0]
	v_pk_mul_f32 v[240:241], v[96:97], v[134:135] op_sel:[1,1] op_sel_hi:[0,1]
	v_pk_fma_f32 v[72:73], v[72:73], v[124:125], v[224:225] op_sel_hi:[1,0,1] neg_lo:[0,0,1]
	v_pk_fma_f32 v[98:99], v[98:99], v[124:125], v[226:227] op_sel:[0,1,0] op_sel_hi:[1,1,1] neg_lo:[0,0,1]
	v_pk_fma_f32 v[74:75], v[74:75], v[126:127], v[238:239] op_sel_hi:[1,0,1] neg_lo:[0,0,1]
	v_pk_fma_f32 v[96:97], v[96:97], v[126:127], v[240:241] op_sel:[0,1,0] op_sel_hi:[1,1,1] neg_lo:[0,0,1]
.LBB0_159:
	s_or_b64 exec, exec, s[28:29]
	v_readlane_b32 s21, v255, 18
	v_mov_b32_e32 v66, v160
	v_mov_b32_e32 v67, v160
	v_mad_i64_i32 v[64:65], s[28:29], v210, s21, 0
	v_lshl_add_u64 v[64:65], v[64:65], 1, s[96:97]
	v_pk_mul_f32 v[98:99], v[66:67], v[98:99]
	v_pk_mul_f32 v[72:73], v[160:161], v[72:73]
	v_pk_mul_f32 v[96:97], v[66:67], v[96:97]
	v_pk_mul_f32 v[74:75], v[160:161], v[74:75]
	v_lshl_add_u64 v[64:65], v[208:209], 1, v[64:65]
	v_cvt_pk_bf16_f32 v72, v72, v73
	v_cvt_pk_bf16_f32 v73, v98, v99
	v_cvt_pk_bf16_f32 v74, v74, v75
	v_cvt_pk_bf16_f32 v75, v96, v97
	v_pk_add_f32 v[54:55], v[54:55], v[62:63]
	v_pk_add_f32 v[52:53], v[52:53], v[60:61]
	v_pk_add_f32 v[50:51], v[50:51], v[58:59]
	v_pk_add_f32 v[48:49], v[48:49], v[56:57]
	global_store_dwordx4 v[64:65], v[72:75], off
	s_and_saveexec_b64 s[28:29], s[8:9]
	s_cbranch_execz .LBB0_161
	v_pk_mul_f32 v[224:225], v[52:53], v[132:133] op_sel:[1,0] op_sel_hi:[0,0]
	v_pk_mul_f32 v[226:227], v[54:55], v[132:133] op_sel:[1,1] op_sel_hi:[0,1]
	v_pk_mul_f32 v[238:239], v[48:49], v[134:135] op_sel:[1,0] op_sel_hi:[0,0]
	v_pk_mul_f32 v[240:241], v[50:51], v[134:135] op_sel:[1,1] op_sel_hi:[0,1]
	v_pk_fma_f32 v[52:53], v[52:53], v[124:125], v[224:225] op_sel_hi:[1,0,1] neg_lo:[0,0,1]
	v_pk_fma_f32 v[54:55], v[54:55], v[124:125], v[226:227] op_sel:[0,1,0] op_sel_hi:[1,1,1] neg_lo:[0,0,1]
	v_pk_fma_f32 v[48:49], v[48:49], v[126:127], v[238:239] op_sel_hi:[1,0,1] neg_lo:[0,0,1]
	v_pk_fma_f32 v[50:51], v[50:51], v[126:127], v[240:241] op_sel:[0,1,0] op_sel_hi:[1,1,1] neg_lo:[0,0,1]
.LBB0_161:
	s_or_b64 exec, exec, s[28:29]
	v_pk_mul_f32 v[54:55], v[66:67], v[54:55]
	v_pk_mul_f32 v[52:53], v[160:161], v[52:53]
	v_pk_mul_f32 v[66:67], v[66:67], v[50:51]
	v_pk_mul_f32 v[50:51], v[160:161], v[48:49]
	v_cvt_pk_bf16_f32 v48, v52, v53
	v_cvt_pk_bf16_f32 v49, v54, v55
	v_cvt_pk_bf16_f32 v50, v50, v51
	v_cvt_pk_bf16_f32 v51, v66, v67
	global_store_dwordx4 v[64:65], v[48:51], off offset:256
	v_pk_add_f32 v[44:45], v[44:45], v[76:77]
	s_nop 0
	v_pk_add_f32 v[50:51], v[46:47], v[78:79]
	v_pk_add_f32 v[48:49], v[42:43], v[70:71]
	v_pk_add_f32 v[46:47], v[40:41], v[68:69]
	s_and_saveexec_b64 s[28:29], s[8:9]
	s_cbranch_execz .LBB0_163
	v_pk_mul_f32 v[224:225], v[44:45], v[108:109] op_sel:[1,0] op_sel_hi:[0,0]
	v_pk_mul_f32 v[226:227], v[50:51], v[108:109] op_sel:[1,1] op_sel_hi:[0,1]
	v_pk_mul_f32 v[238:239], v[46:47], v[110:111] op_sel:[1,0] op_sel_hi:[0,0]
	v_pk_mul_f32 v[240:241], v[48:49], v[110:111] op_sel:[1,1] op_sel_hi:[0,1]
	v_pk_fma_f32 v[44:45], v[44:45], v[104:105], v[224:225] op_sel_hi:[1,0,1] neg_lo:[0,0,1]
	v_pk_fma_f32 v[50:51], v[50:51], v[104:105], v[226:227] op_sel:[0,1,0] op_sel_hi:[1,1,1] neg_lo:[0,0,1]
	v_pk_fma_f32 v[46:47], v[46:47], v[106:107], v[238:239] op_sel_hi:[1,0,1] neg_lo:[0,0,1]
	v_pk_fma_f32 v[48:49], v[48:49], v[106:107], v[240:241] op_sel:[0,1,0] op_sel_hi:[1,1,1] neg_lo:[0,0,1]
.LBB0_163:
	s_or_b64 exec, exec, s[28:29]
	v_add_u32_e32 v40, 16, v210
	v_readlane_b32 s21, v255, 18
	v_mov_b32_e32 v42, v160
	v_mov_b32_e32 v43, v160
	v_mad_i64_i32 v[40:41], s[28:29], v40, s21, 0
	v_lshl_add_u64 v[40:41], v[40:41], 1, s[96:97]
	v_pk_mul_f32 v[50:51], v[42:43], v[50:51]
	v_pk_mul_f32 v[44:45], v[160:161], v[44:45]
	v_pk_mul_f32 v[48:49], v[42:43], v[48:49]
	v_pk_mul_f32 v[46:47], v[160:161], v[46:47]
	v_lshl_add_u64 v[40:41], v[208:209], 1, v[40:41]
	v_cvt_pk_bf16_f32 v44, v44, v45
	v_cvt_pk_bf16_f32 v45, v50, v51
	v_cvt_pk_bf16_f32 v46, v46, v47
	v_cvt_pk_bf16_f32 v47, v48, v49
	v_pk_add_f32 v[38:39], v[38:39], v[62:63]
	v_pk_add_f32 v[36:37], v[36:37], v[60:61]
	v_pk_add_f32 v[34:35], v[34:35], v[58:59]
	v_pk_add_f32 v[32:33], v[32:33], v[56:57]
	global_store_dwordx4 v[40:41], v[44:47], off
	s_and_saveexec_b64 s[28:29], s[8:9]
	s_cbranch_execz .LBB0_165
	v_pk_mul_f32 v[224:225], v[36:37], v[108:109] op_sel:[1,0] op_sel_hi:[0,0]
	v_pk_mul_f32 v[226:227], v[38:39], v[108:109] op_sel:[1,1] op_sel_hi:[0,1]
	v_pk_mul_f32 v[238:239], v[32:33], v[110:111] op_sel:[1,0] op_sel_hi:[0,0]
	v_pk_mul_f32 v[240:241], v[34:35], v[110:111] op_sel:[1,1] op_sel_hi:[0,1]
	v_pk_fma_f32 v[36:37], v[36:37], v[104:105], v[224:225] op_sel_hi:[1,0,1] neg_lo:[0,0,1]
	v_pk_fma_f32 v[38:39], v[38:39], v[104:105], v[226:227] op_sel:[0,1,0] op_sel_hi:[1,1,1] neg_lo:[0,0,1]
	v_pk_fma_f32 v[32:33], v[32:33], v[106:107], v[238:239] op_sel_hi:[1,0,1] neg_lo:[0,0,1]
	v_pk_fma_f32 v[34:35], v[34:35], v[106:107], v[240:241] op_sel:[0,1,0] op_sel_hi:[1,1,1] neg_lo:[0,0,1]
.LBB0_165:
	s_or_b64 exec, exec, s[28:29]
	v_pk_mul_f32 v[38:39], v[42:43], v[38:39]
	v_pk_mul_f32 v[36:37], v[160:161], v[36:37]
	v_pk_mul_f32 v[42:43], v[42:43], v[34:35]
	v_pk_mul_f32 v[34:35], v[160:161], v[32:33]
	v_cvt_pk_bf16_f32 v32, v36, v37
	v_cvt_pk_bf16_f32 v33, v38, v39
	v_cvt_pk_bf16_f32 v34, v34, v35
	v_cvt_pk_bf16_f32 v35, v42, v43
	global_store_dwordx4 v[40:41], v[32:35], off offset:256
	v_pk_add_f32 v[28:29], v[28:29], v[76:77]
	s_nop 0
	v_pk_add_f32 v[34:35], v[30:31], v[78:79]
	v_pk_add_f32 v[32:33], v[26:27], v[70:71]
	v_pk_add_f32 v[30:31], v[24:25], v[68:69]
	s_and_saveexec_b64 s[28:29], s[8:9]
	s_cbranch_execz .LBB0_167
	s_waitcnt vmcnt(6)
	v_pk_mul_f32 v[224:225], v[28:29], v[92:93] op_sel:[1,0] op_sel_hi:[0,0]
	v_pk_mul_f32 v[226:227], v[34:35], v[92:93] op_sel:[1,1] op_sel_hi:[0,1]
	v_pk_mul_f32 v[238:239], v[30:31], v[94:95] op_sel:[1,0] op_sel_hi:[0,0]
	v_pk_mul_f32 v[240:241], v[32:33], v[94:95] op_sel:[1,1] op_sel_hi:[0,1]
	v_pk_fma_f32 v[28:29], v[28:29], v[88:89], v[224:225] op_sel_hi:[1,0,1] neg_lo:[0,0,1]
	v_pk_fma_f32 v[34:35], v[34:35], v[88:89], v[226:227] op_sel:[0,1,0] op_sel_hi:[1,1,1] neg_lo:[0,0,1]
	v_pk_fma_f32 v[30:31], v[30:31], v[90:91], v[238:239] op_sel_hi:[1,0,1] neg_lo:[0,0,1]
	v_pk_fma_f32 v[32:33], v[32:33], v[90:91], v[240:241] op_sel:[0,1,0] op_sel_hi:[1,1,1] neg_lo:[0,0,1]
.LBB0_167:
	s_or_b64 exec, exec, s[28:29]
	v_add_u32_e32 v24, 32, v210
	v_readlane_b32 s21, v255, 18
	v_mov_b32_e32 v26, v160
	v_mov_b32_e32 v27, v160
	v_mad_i64_i32 v[24:25], s[28:29], v24, s21, 0
	v_lshl_add_u64 v[24:25], v[24:25], 1, s[96:97]
	v_pk_mul_f32 v[34:35], v[26:27], v[34:35]
	v_pk_mul_f32 v[28:29], v[160:161], v[28:29]
	v_pk_mul_f32 v[32:33], v[26:27], v[32:33]
	v_pk_mul_f32 v[30:31], v[160:161], v[30:31]
	v_lshl_add_u64 v[24:25], v[208:209], 1, v[24:25]
	v_cvt_pk_bf16_f32 v28, v28, v29
	v_cvt_pk_bf16_f32 v29, v34, v35
	v_cvt_pk_bf16_f32 v30, v30, v31
	v_cvt_pk_bf16_f32 v31, v32, v33
	v_pk_add_f32 v[22:23], v[22:23], v[62:63]
	v_pk_add_f32 v[20:21], v[20:21], v[60:61]
	v_pk_add_f32 v[18:19], v[18:19], v[58:59]
	v_pk_add_f32 v[16:17], v[16:17], v[56:57]
	global_store_dwordx4 v[24:25], v[28:31], off
	s_and_saveexec_b64 s[28:29], s[8:9]
	s_cbranch_execz .LBB0_169
	s_waitcnt vmcnt(7)
	v_pk_mul_f32 v[224:225], v[20:21], v[92:93] op_sel:[1,0] op_sel_hi:[0,0]
	v_pk_mul_f32 v[226:227], v[22:23], v[92:93] op_sel:[1,1] op_sel_hi:[0,1]
	v_pk_mul_f32 v[238:239], v[16:17], v[94:95] op_sel:[1,0] op_sel_hi:[0,0]
	v_pk_mul_f32 v[240:241], v[18:19], v[94:95] op_sel:[1,1] op_sel_hi:[0,1]
	v_pk_fma_f32 v[20:21], v[20:21], v[88:89], v[224:225] op_sel_hi:[1,0,1] neg_lo:[0,0,1]
	v_pk_fma_f32 v[22:23], v[22:23], v[88:89], v[226:227] op_sel:[0,1,0] op_sel_hi:[1,1,1] neg_lo:[0,0,1]
	v_pk_fma_f32 v[16:17], v[16:17], v[90:91], v[238:239] op_sel_hi:[1,0,1] neg_lo:[0,0,1]
	v_pk_fma_f32 v[18:19], v[18:19], v[90:91], v[240:241] op_sel:[0,1,0] op_sel_hi:[1,1,1] neg_lo:[0,0,1]
.LBB0_169:
	s_or_b64 exec, exec, s[28:29]
	v_pk_mul_f32 v[22:23], v[26:27], v[22:23]
	v_pk_mul_f32 v[20:21], v[160:161], v[20:21]
	v_pk_mul_f32 v[26:27], v[26:27], v[18:19]
	v_pk_mul_f32 v[18:19], v[160:161], v[16:17]
	v_cvt_pk_bf16_f32 v16, v20, v21
	v_cvt_pk_bf16_f32 v17, v22, v23
	v_cvt_pk_bf16_f32 v18, v18, v19
	v_cvt_pk_bf16_f32 v19, v26, v27
	global_store_dwordx4 v[24:25], v[16:19], off offset:256
	v_pk_add_f32 v[12:13], v[12:13], v[76:77]
	s_nop 0
	v_pk_add_f32 v[18:19], v[14:15], v[78:79]
	v_pk_add_f32 v[16:17], v[10:11], v[70:71]
	v_pk_add_f32 v[14:15], v[8:9], v[68:69]
	s_and_saveexec_b64 s[28:29], s[8:9]
	s_cbranch_execz .LBB0_171
	s_waitcnt vmcnt(6)
	v_pk_mul_f32 v[224:225], v[12:13], v[84:85] op_sel:[1,0] op_sel_hi:[0,0]
	v_pk_mul_f32 v[226:227], v[18:19], v[84:85] op_sel:[1,1] op_sel_hi:[0,1]
	v_pk_mul_f32 v[238:239], v[14:15], v[86:87] op_sel:[1,0] op_sel_hi:[0,0]
	v_pk_mul_f32 v[240:241], v[16:17], v[86:87] op_sel:[1,1] op_sel_hi:[0,1]
	v_pk_fma_f32 v[12:13], v[12:13], v[80:81], v[224:225] op_sel_hi:[1,0,1] neg_lo:[0,0,1]
	v_pk_fma_f32 v[18:19], v[18:19], v[80:81], v[226:227] op_sel:[0,1,0] op_sel_hi:[1,1,1] neg_lo:[0,0,1]
	v_pk_fma_f32 v[14:15], v[14:15], v[82:83], v[238:239] op_sel_hi:[1,0,1] neg_lo:[0,0,1]
	v_pk_fma_f32 v[16:17], v[16:17], v[82:83], v[240:241] op_sel:[0,1,0] op_sel_hi:[1,1,1] neg_lo:[0,0,1]
.LBB0_171:
	s_or_b64 exec, exec, s[28:29]
	v_add_u32_e32 v8, 48, v210
	v_readlane_b32 s21, v255, 18
	v_mov_b32_e32 v10, v160
	v_mov_b32_e32 v11, v160
	v_mad_i64_i32 v[8:9], s[28:29], v8, s21, 0
	v_lshl_add_u64 v[8:9], v[8:9], 1, s[96:97]
	v_pk_mul_f32 v[18:19], v[10:11], v[18:19]
	v_pk_mul_f32 v[12:13], v[160:161], v[12:13]
	v_pk_mul_f32 v[16:17], v[10:11], v[16:17]
	v_pk_mul_f32 v[14:15], v[160:161], v[14:15]
	v_lshl_add_u64 v[8:9], v[208:209], 1, v[8:9]
	v_cvt_pk_bf16_f32 v12, v12, v13
	v_cvt_pk_bf16_f32 v13, v18, v19
	v_cvt_pk_bf16_f32 v14, v14, v15
	v_cvt_pk_bf16_f32 v15, v16, v17
	v_pk_add_f32 v[6:7], v[6:7], v[62:63]
	v_pk_add_f32 v[4:5], v[4:5], v[60:61]
	v_pk_add_f32 v[2:3], v[2:3], v[58:59]
	v_pk_add_f32 v[0:1], v[0:1], v[56:57]
	global_store_dwordx4 v[8:9], v[12:15], off
	s_and_saveexec_b64 s[28:29], s[8:9]
	s_cbranch_execz .LBB0_173
	s_waitcnt vmcnt(7)
	v_pk_mul_f32 v[224:225], v[4:5], v[84:85] op_sel:[1,0] op_sel_hi:[0,0]
	v_pk_mul_f32 v[226:227], v[6:7], v[84:85] op_sel:[1,1] op_sel_hi:[0,1]
	v_pk_mul_f32 v[238:239], v[0:1], v[86:87] op_sel:[1,0] op_sel_hi:[0,0]
	v_pk_mul_f32 v[240:241], v[2:3], v[86:87] op_sel:[1,1] op_sel_hi:[0,1]
	v_pk_fma_f32 v[4:5], v[4:5], v[80:81], v[224:225] op_sel_hi:[1,0,1] neg_lo:[0,0,1]
	v_pk_fma_f32 v[6:7], v[6:7], v[80:81], v[226:227] op_sel:[0,1,0] op_sel_hi:[1,1,1] neg_lo:[0,0,1]
	v_pk_fma_f32 v[0:1], v[0:1], v[82:83], v[238:239] op_sel_hi:[1,0,1] neg_lo:[0,0,1]
	v_pk_fma_f32 v[2:3], v[2:3], v[82:83], v[240:241] op_sel:[0,1,0] op_sel_hi:[1,1,1] neg_lo:[0,0,1]
